# v025 + Swiglu next-tile rstd: rsqrt denormal-input guard removed (argument is sum/DM + 1e-6, never denormal), two v_rsq instead of 13 instructions
# baseline (speedup 1.0000x reference)
; __device__ __forceinline__ unsigned pk_bf16(float lo, float hi) { f32x2 v = {lo, hi}; bf16x2_t b = __builtin_convertvector(v, bf16x2_t); return __builtin_bit_cast(unsigned, b); }
; __device__ __forceinline__ float fast_exp2(float x) { return __builtin_amdgcn_exp2f(x); }
; __device__ __forceinline__ float fast_rcp(float x) { return __builtin_amdgcn_rcpf(x); }
;     __device__ __forceinline__ void operator()(const f32x4 (&acc)[2][2][4][2], const Unit& u, int wr, int wc, int fr, int fq, float rp0, float rp1, const f32x4& raw0, const f32x4& raw1, float& rn0, float& rn1) const {
;     ...
;         for (int k = 0; k < 8; ++k) rs[k] = __shfl((k >> 2) ? rp1 : rp0, fr + 16 * (k & 3));
; #pragma unroll
;         for (int ai = 0; ai < 2; ++ai)
; #pragma unroll
;             for (int m = 0; m < 4; ++m) {
;                 const int row = row0 + ai * HALF + m * 16; const float r = rs[ai * 4 + m];
;                 const float c1 = -1.4426950408889634f * r, r2 = r * r;
;                 const f32x4 ga = acc[ai][0][m][0], gb = acc[ai][0][m][1];
;                 const f32x4 ta = ga * c1, tb = gb * c1;
;                 f32x4 ea, eb;
; #pragma unroll
;                 for (int j = 0; j < 4; ++j) { ea[j] = fast_exp2(ta[j]); eb[j] = fast_exp2(tb[j]); }
;                 const f32x4 da = ea + 1.f, db = eb + 1.f;
;                 f32x4 qa, qb;
; #pragma unroll
;                 for (int j = 0; j < 4; ++j) { qa[j] = fast_rcp(da[j]); qb[j] = fast_rcp(db[j]); }
;                 const f32x4 oa = ((ga * acc[ai][1][m][0]) * r2) * qa, ob = ((gb * acc[ai][1][m][1]) * r2) * qb;
;                 u32x4 w;
;                 w.x = pk_bf16(oa[0], oa[1]); w.y = pk_bf16(oa[2], oa[3]); w.z = pk_bf16(ob[0], ob[1]); w.w = pk_bf16(ob[2], ob[3]);
;                 if (ai == 0 && m == 0) rstd_finish(raw0, raw1, rn0, rn1);
;                 *(u32x4*)(O + (size_t)row * FF + col0) = w;
.LBB0_322:
	s_andn2_b64 vcc, exec, s[4:5]
	s_mov_b64 s[4:5], -1
	v_and_or_b32 v157, v197, 64, v154
	v_lshlrev_b32_e32 v157, 2, v157
	ds_bpermute_b32 v162, v157, v144
	ds_bpermute_b32 v200, v157, v252
	ds_bpermute_b32 v163, v157, v144 offset:64
	ds_bpermute_b32 v202, v157, v252 offset:64
	ds_bpermute_b32 v164, v157, v144 offset:128
	ds_bpermute_b32 v204, v157, v252 offset:128
	ds_bpermute_b32 v165, v157, v144 offset:192
	ds_bpermute_b32 v206, v157, v252 offset:192
	ds_bpermute_b32 v166, v157, v145
	ds_bpermute_b32 v220, v157, v253
	ds_bpermute_b32 v167, v157, v145 offset:64
	ds_bpermute_b32 v222, v157, v253 offset:64
	ds_bpermute_b32 v168, v157, v145 offset:128
	ds_bpermute_b32 v224, v157, v253 offset:128
	ds_bpermute_b32 v169, v157, v145 offset:192
	ds_bpermute_b32 v226, v157, v253 offset:192
	v_lshl_add_u32 v153, s6, 8, v155
	v_lshl_or_b32 v160, s7, 7, v151
	v_mul_u32_u24_e32 v161, 0x1600, v153
	v_lshl_add_u32 v161, v160, 1, v161
	v_pk_mul_f32 v[126:127], v[118:119], v[126:127]
	v_pk_mul_f32 v[128:129], v[120:121], v[128:129]
	s_waitcnt lgkmcnt(14)
	v_mul_f32_e32 v228, 0xbfb8aa3b, v162
	v_pk_mul_f32 v[122:123], v[114:115], v[122:123]
	v_pk_mul_f32 v[124:125], v[116:117], v[124:125]
	v_pk_mul_f32 v[118:119], v[118:119], v[228:229] op_sel_hi:[1,0]
	v_pk_mul_f32 v[120:121], v[120:121], v[228:229] op_sel_hi:[1,0]
	v_pk_mul_f32 v[114:115], v[114:115], v[228:229] op_sel_hi:[1,0]
	v_pk_mul_f32 v[116:117], v[116:117], v[228:229] op_sel_hi:[1,0]
	v_exp_f32_e32 v118, v118
	v_exp_f32_e32 v119, v119
	v_exp_f32_e32 v120, v120
	v_exp_f32_e32 v121, v121
	v_exp_f32_e32 v114, v114
	v_exp_f32_e32 v115, v115
	v_exp_f32_e32 v116, v116
	v_exp_f32_e32 v117, v117
	v_pk_fma_f32 v[118:119], v[118:119], v[200:201], v[200:201] op_sel_hi:[1,0,0]
	v_pk_fma_f32 v[120:121], v[120:121], v[200:201], v[200:201] op_sel_hi:[1,0,0]
	v_pk_fma_f32 v[114:115], v[114:115], v[200:201], v[200:201] op_sel_hi:[1,0,0]
	v_pk_fma_f32 v[116:117], v[116:117], v[200:201], v[200:201] op_sel_hi:[1,0,0]
	v_rcp_f32_e32 v118, v118
	v_rcp_f32_e32 v119, v119
	v_rcp_f32_e32 v120, v120
	v_rcp_f32_e32 v121, v121
	v_rcp_f32_e32 v114, v114
	v_rcp_f32_e32 v115, v115
	v_rcp_f32_e32 v116, v116
	v_rcp_f32_e32 v117, v117
	v_pk_mul_f32 v[126:127], v[126:127], v[118:119]
	v_pk_mul_f32 v[128:129], v[128:129], v[120:121]
	v_pk_mul_f32 v[122:123], v[122:123], v[114:115]
	v_pk_mul_f32 v[124:125], v[124:125], v[116:117]
	v_cvt_pk_bf16_f32 v118, v126, v127
	v_cvt_pk_bf16_f32 v119, v128, v129
	v_cvt_pk_bf16_f32 v120, v122, v123
	v_cvt_pk_bf16_f32 v121, v124, v125
	global_store_dwordx4 v161, v[118:121], s[24:25]
	v_pk_mul_f32 v[110:111], v[102:103], v[110:111]
	v_pk_mul_f32 v[112:113], v[104:105], v[112:113]
	s_waitcnt lgkmcnt(12)
	v_mul_f32_e32 v228, 0xbfb8aa3b, v163
	v_pk_mul_f32 v[106:107], v[98:99], v[106:107]
	v_pk_mul_f32 v[108:109], v[100:101], v[108:109]
	v_pk_mul_f32 v[102:103], v[102:103], v[228:229] op_sel_hi:[1,0]
	v_pk_mul_f32 v[104:105], v[104:105], v[228:229] op_sel_hi:[1,0]
	v_pk_mul_f32 v[98:99], v[98:99], v[228:229] op_sel_hi:[1,0]
	v_pk_mul_f32 v[100:101], v[100:101], v[228:229] op_sel_hi:[1,0]
	v_exp_f32_e32 v102, v102
	v_exp_f32_e32 v103, v103
	v_exp_f32_e32 v104, v104
	v_exp_f32_e32 v105, v105
	v_exp_f32_e32 v98, v98
	v_exp_f32_e32 v99, v99
	v_exp_f32_e32 v100, v100
	v_exp_f32_e32 v101, v101
	v_pk_fma_f32 v[102:103], v[102:103], v[202:203], v[202:203] op_sel_hi:[1,0,0]
	v_pk_fma_f32 v[104:105], v[104:105], v[202:203], v[202:203] op_sel_hi:[1,0,0]
	v_pk_fma_f32 v[98:99], v[98:99], v[202:203], v[202:203] op_sel_hi:[1,0,0]
	v_pk_fma_f32 v[100:101], v[100:101], v[202:203], v[202:203] op_sel_hi:[1,0,0]
	v_rcp_f32_e32 v102, v102
	v_rcp_f32_e32 v103, v103
	v_rcp_f32_e32 v104, v104
	v_rcp_f32_e32 v105, v105
	v_rcp_f32_e32 v98, v98
	v_rcp_f32_e32 v99, v99
	v_rcp_f32_e32 v100, v100
	v_rcp_f32_e32 v101, v101
	v_pk_mul_f32 v[110:111], v[110:111], v[102:103]
	v_pk_mul_f32 v[112:113], v[112:113], v[104:105]
	v_pk_mul_f32 v[106:107], v[106:107], v[98:99]
	v_pk_mul_f32 v[108:109], v[108:109], v[100:101]
	v_cvt_pk_bf16_f32 v102, v110, v111
	v_cvt_pk_bf16_f32 v103, v112, v113
	v_cvt_pk_bf16_f32 v104, v106, v107
	v_cvt_pk_bf16_f32 v105, v108, v109
	v_add_u32_e32 v170, 0x16000, v161
	global_store_dwordx4 v170, v[102:105], s[24:25]
	v_pk_mul_f32 v[94:95], v[86:87], v[94:95]
	v_pk_mul_f32 v[96:97], v[88:89], v[96:97]
	s_waitcnt lgkmcnt(10)
	v_mul_f32_e32 v228, 0xbfb8aa3b, v164
	v_pk_mul_f32 v[90:91], v[82:83], v[90:91]
	v_pk_mul_f32 v[92:93], v[84:85], v[92:93]
	v_pk_mul_f32 v[86:87], v[86:87], v[228:229] op_sel_hi:[1,0]
	v_pk_mul_f32 v[88:89], v[88:89], v[228:229] op_sel_hi:[1,0]
	v_pk_mul_f32 v[82:83], v[82:83], v[228:229] op_sel_hi:[1,0]
	v_pk_mul_f32 v[84:85], v[84:85], v[228:229] op_sel_hi:[1,0]
	v_exp_f32_e32 v86, v86
	v_exp_f32_e32 v87, v87
	v_exp_f32_e32 v88, v88
	v_exp_f32_e32 v89, v89
	v_exp_f32_e32 v82, v82
	v_exp_f32_e32 v83, v83
	v_exp_f32_e32 v84, v84
	v_exp_f32_e32 v85, v85
	v_pk_fma_f32 v[86:87], v[86:87], v[204:205], v[204:205] op_sel_hi:[1,0,0]
	v_pk_fma_f32 v[88:89], v[88:89], v[204:205], v[204:205] op_sel_hi:[1,0,0]
	v_pk_fma_f32 v[82:83], v[82:83], v[204:205], v[204:205] op_sel_hi:[1,0,0]
	v_pk_fma_f32 v[84:85], v[84:85], v[204:205], v[204:205] op_sel_hi:[1,0,0]
	v_rcp_f32_e32 v86, v86
	v_rcp_f32_e32 v87, v87
	v_rcp_f32_e32 v88, v88
	v_rcp_f32_e32 v89, v89
	v_rcp_f32_e32 v82, v82
	v_rcp_f32_e32 v83, v83
	v_rcp_f32_e32 v84, v84
	v_rcp_f32_e32 v85, v85
	v_pk_mul_f32 v[94:95], v[94:95], v[86:87]
	v_pk_mul_f32 v[96:97], v[96:97], v[88:89]
	v_pk_mul_f32 v[90:91], v[90:91], v[82:83]
	v_pk_mul_f32 v[92:93], v[92:93], v[84:85]
	v_cvt_pk_bf16_f32 v86, v94, v95
	v_cvt_pk_bf16_f32 v87, v96, v97
	v_cvt_pk_bf16_f32 v88, v90, v91
	v_cvt_pk_bf16_f32 v89, v92, v93
	v_add_u32_e32 v170, 0x2c000, v161
	global_store_dwordx4 v170, v[86:89], s[24:25]
	v_pk_mul_f32 v[78:79], v[70:71], v[78:79]
	v_pk_mul_f32 v[80:81], v[72:73], v[80:81]
	s_waitcnt lgkmcnt(8)
; __device__ __forceinline__ unsigned pk_bf16(float lo, float hi) { f32x2 v = {lo, hi}; bf16x2_t b = __builtin_convertvector(v, bf16x2_t); return __builtin_bit_cast(unsigned, b); }
; __device__ __forceinline__ float fast_exp2(float x) { return __builtin_amdgcn_exp2f(x); }
; __device__ __forceinline__ float fast_rcp(float x) { return __builtin_amdgcn_rcpf(x); }
;     __device__ __forceinline__ void operator()(const f32x4 (&acc)[2][2][4][2], const Unit& u, int wr, int wc, int fr, int fq, float rp0, float rp1, const f32x4& raw0, const f32x4& raw1, float& rn0, float& rn1) const {
;     ...
;                 const int row = row0 + ai * HALF + m * 16; const float r = rs[ai * 4 + m];
;                 const float c1 = -1.4426950408889634f * r, r2 = r * r;
;                 const f32x4 ga = acc[ai][0][m][0], gb = acc[ai][0][m][1];
;                 const f32x4 ta = ga * c1, tb = gb * c1;
;                 f32x4 ea, eb;
; #pragma unroll
;                 for (int j = 0; j < 4; ++j) { ea[j] = fast_exp2(ta[j]); eb[j] = fast_exp2(tb[j]); }
;                 const f32x4 da = ea + 1.f, db = eb + 1.f;
;                 f32x4 qa, qb;
; #pragma unroll
;                 for (int j = 0; j < 4; ++j) { qa[j] = fast_rcp(da[j]); qb[j] = fast_rcp(db[j]); }
;                 const f32x4 oa = ((ga * acc[ai][1][m][0]) * r2) * qa, ob = ((gb * acc[ai][1][m][1]) * r2) * qb;
;                 u32x4 w;
;                 w.x = pk_bf16(oa[0], oa[1]); w.y = pk_bf16(oa[2], oa[3]); w.z = pk_bf16(ob[0], ob[1]); w.w = pk_bf16(ob[2], ob[3]);
;                 if (ai == 0 && m == 0) rstd_finish(raw0, raw1, rn0, rn1);
;                 *(u32x4*)(O + (size_t)row * FF + col0) = w;
	v_mul_f32_e32 v228, 0xbfb8aa3b, v165
	v_pk_mul_f32 v[74:75], v[62:63], v[74:75]
	v_pk_mul_f32 v[76:77], v[64:65], v[76:77]
	v_pk_mul_f32 v[70:71], v[70:71], v[228:229] op_sel_hi:[1,0]
	v_pk_mul_f32 v[72:73], v[72:73], v[228:229] op_sel_hi:[1,0]
	v_pk_mul_f32 v[62:63], v[62:63], v[228:229] op_sel_hi:[1,0]
	v_pk_mul_f32 v[64:65], v[64:65], v[228:229] op_sel_hi:[1,0]
	v_exp_f32_e32 v70, v70
	v_exp_f32_e32 v71, v71
	v_exp_f32_e32 v72, v72
	v_exp_f32_e32 v73, v73
	v_exp_f32_e32 v62, v62
	v_exp_f32_e32 v63, v63
	v_exp_f32_e32 v64, v64
	v_exp_f32_e32 v65, v65
	v_pk_fma_f32 v[70:71], v[70:71], v[206:207], v[206:207] op_sel_hi:[1,0,0]
	v_pk_fma_f32 v[72:73], v[72:73], v[206:207], v[206:207] op_sel_hi:[1,0,0]
	v_pk_fma_f32 v[62:63], v[62:63], v[206:207], v[206:207] op_sel_hi:[1,0,0]
	v_pk_fma_f32 v[64:65], v[64:65], v[206:207], v[206:207] op_sel_hi:[1,0,0]
	v_rcp_f32_e32 v70, v70
	v_rcp_f32_e32 v71, v71
	v_rcp_f32_e32 v72, v72
	v_rcp_f32_e32 v73, v73
	v_rcp_f32_e32 v62, v62
	v_rcp_f32_e32 v63, v63
	v_rcp_f32_e32 v64, v64
	v_rcp_f32_e32 v65, v65
	v_pk_mul_f32 v[78:79], v[78:79], v[70:71]
	v_pk_mul_f32 v[80:81], v[80:81], v[72:73]
	v_pk_mul_f32 v[74:75], v[74:75], v[62:63]
	v_pk_mul_f32 v[76:77], v[76:77], v[64:65]
	v_cvt_pk_bf16_f32 v70, v78, v79
	v_cvt_pk_bf16_f32 v71, v80, v81
	v_cvt_pk_bf16_f32 v72, v74, v75
	v_cvt_pk_bf16_f32 v73, v76, v77
	v_add_u32_e32 v170, 0x42000, v161
	global_store_dwordx4 v170, v[70:73], s[24:25]
	v_pk_mul_f32 v[66:67], v[54:55], v[66:67]
	v_pk_mul_f32 v[68:69], v[56:57], v[68:69]
	s_waitcnt lgkmcnt(6)
	v_mul_f32_e32 v228, 0xbfb8aa3b, v166
	v_pk_mul_f32 v[58:59], v[50:51], v[58:59]
	v_pk_mul_f32 v[60:61], v[52:53], v[60:61]
	v_pk_mul_f32 v[54:55], v[54:55], v[228:229] op_sel_hi:[1,0]
	v_pk_mul_f32 v[56:57], v[56:57], v[228:229] op_sel_hi:[1,0]
	v_pk_mul_f32 v[50:51], v[50:51], v[228:229] op_sel_hi:[1,0]
	v_pk_mul_f32 v[52:53], v[52:53], v[228:229] op_sel_hi:[1,0]
	v_exp_f32_e32 v54, v54
	v_exp_f32_e32 v55, v55
	v_exp_f32_e32 v56, v56
	v_exp_f32_e32 v57, v57
	v_exp_f32_e32 v50, v50
	v_exp_f32_e32 v51, v51
	v_exp_f32_e32 v52, v52
	v_exp_f32_e32 v53, v53
	v_pk_fma_f32 v[54:55], v[54:55], v[220:221], v[220:221] op_sel_hi:[1,0,0]
	v_pk_fma_f32 v[56:57], v[56:57], v[220:221], v[220:221] op_sel_hi:[1,0,0]
	v_pk_fma_f32 v[50:51], v[50:51], v[220:221], v[220:221] op_sel_hi:[1,0,0]
	v_pk_fma_f32 v[52:53], v[52:53], v[220:221], v[220:221] op_sel_hi:[1,0,0]
	v_rcp_f32_e32 v54, v54
	v_rcp_f32_e32 v55, v55
	v_rcp_f32_e32 v56, v56
	v_rcp_f32_e32 v57, v57
	v_rcp_f32_e32 v50, v50
	v_rcp_f32_e32 v51, v51
	v_rcp_f32_e32 v52, v52
	v_rcp_f32_e32 v53, v53
	v_pk_mul_f32 v[66:67], v[66:67], v[54:55]
	v_pk_mul_f32 v[68:69], v[68:69], v[56:57]
	v_pk_mul_f32 v[58:59], v[58:59], v[50:51]
	v_pk_mul_f32 v[60:61], v[60:61], v[52:53]
	v_cvt_pk_bf16_f32 v54, v66, v67
	v_cvt_pk_bf16_f32 v55, v68, v69
	v_cvt_pk_bf16_f32 v56, v58, v59
	v_cvt_pk_bf16_f32 v57, v60, v61
	v_add_u32_e32 v170, 0xb0000, v161
	global_store_dwordx4 v170, v[54:57], s[24:25]
	v_pk_mul_f32 v[46:47], v[38:39], v[46:47]
	v_pk_mul_f32 v[48:49], v[40:41], v[48:49]
	s_waitcnt lgkmcnt(4)
	v_mul_f32_e32 v228, 0xbfb8aa3b, v167
	v_pk_mul_f32 v[42:43], v[34:35], v[42:43]
	v_pk_mul_f32 v[44:45], v[36:37], v[44:45]
	v_pk_mul_f32 v[38:39], v[38:39], v[228:229] op_sel_hi:[1,0]
	v_pk_mul_f32 v[40:41], v[40:41], v[228:229] op_sel_hi:[1,0]
	v_pk_mul_f32 v[34:35], v[34:35], v[228:229] op_sel_hi:[1,0]
	v_pk_mul_f32 v[36:37], v[36:37], v[228:229] op_sel_hi:[1,0]
	v_exp_f32_e32 v38, v38
	v_exp_f32_e32 v39, v39
	v_exp_f32_e32 v40, v40
	v_exp_f32_e32 v41, v41
	v_exp_f32_e32 v34, v34
	v_exp_f32_e32 v35, v35
	v_exp_f32_e32 v36, v36
	v_exp_f32_e32 v37, v37
	v_pk_fma_f32 v[38:39], v[38:39], v[222:223], v[222:223] op_sel_hi:[1,0,0]
	v_pk_fma_f32 v[40:41], v[40:41], v[222:223], v[222:223] op_sel_hi:[1,0,0]
	v_pk_fma_f32 v[34:35], v[34:35], v[222:223], v[222:223] op_sel_hi:[1,0,0]
	v_pk_fma_f32 v[36:37], v[36:37], v[222:223], v[222:223] op_sel_hi:[1,0,0]
	v_rcp_f32_e32 v38, v38
	v_rcp_f32_e32 v39, v39
	v_rcp_f32_e32 v40, v40
	v_rcp_f32_e32 v41, v41
	v_rcp_f32_e32 v34, v34
	v_rcp_f32_e32 v35, v35
	v_rcp_f32_e32 v36, v36
	v_rcp_f32_e32 v37, v37
	v_pk_mul_f32 v[46:47], v[46:47], v[38:39]
	v_pk_mul_f32 v[48:49], v[48:49], v[40:41]
	v_pk_mul_f32 v[42:43], v[42:43], v[34:35]
	v_pk_mul_f32 v[44:45], v[44:45], v[36:37]
	v_cvt_pk_bf16_f32 v38, v46, v47
	v_cvt_pk_bf16_f32 v39, v48, v49
	v_cvt_pk_bf16_f32 v40, v42, v43
	v_cvt_pk_bf16_f32 v41, v44, v45
	v_add_u32_e32 v170, 0xc6000, v161
	global_store_dwordx4 v170, v[38:41], s[24:25]
	v_pk_mul_f32 v[30:31], v[22:23], v[30:31]
	v_pk_mul_f32 v[32:33], v[24:25], v[32:33]
	s_waitcnt lgkmcnt(2)
; __device__ __forceinline__ unsigned pk_bf16(float lo, float hi) { f32x2 v = {lo, hi}; bf16x2_t b = __builtin_convertvector(v, bf16x2_t); return __builtin_bit_cast(unsigned, b); }
; __device__ __forceinline__ float fast_exp2(float x) { return __builtin_amdgcn_exp2f(x); }
; __device__ __forceinline__ float fast_rcp(float x) { return __builtin_amdgcn_rcpf(x); }
; __device__ __forceinline__ void rstd_finish(const f32x4& raw0, const f32x4& raw1, float& rn0, float& rn1) {
;     rn0 = rsqrtf(((raw0.x + raw0.y) + (raw0.z + raw0.w)) * (1.f / DM) + EPS); rn1 = rsqrtf(((raw1.x + raw1.y) + (raw1.z + raw1.w)) * (1.f / DM) + EPS);
;     asm volatile("" :: "v"(rn0), "v"(rn1) : "memory");
;     __device__ __forceinline__ void operator()(const f32x4 (&acc)[2][2][4][2], const Unit& u, int wr, int wc, int fr, int fq, float rp0, float rp1, const f32x4& raw0, const f32x4& raw1, float& rn0, float& rn1) const {
;     ...
;                 const int row = row0 + ai * HALF + m * 16; const float r = rs[ai * 4 + m];
;                 const float c1 = -1.4426950408889634f * r, r2 = r * r;
;                 const f32x4 ga = acc[ai][0][m][0], gb = acc[ai][0][m][1];
;                 const f32x4 ta = ga * c1, tb = gb * c1;
;                 f32x4 ea, eb;
; #pragma unroll
;                 for (int j = 0; j < 4; ++j) { ea[j] = fast_exp2(ta[j]); eb[j] = fast_exp2(tb[j]); }
;                 const f32x4 da = ea + 1.f, db = eb + 1.f;
;                 f32x4 qa, qb;
; #pragma unroll
;                 for (int j = 0; j < 4; ++j) { qa[j] = fast_rcp(da[j]); qb[j] = fast_rcp(db[j]); }
;                 const f32x4 oa = ((ga * acc[ai][1][m][0]) * r2) * qa, ob = ((gb * acc[ai][1][m][1]) * r2) * qb;
;                 u32x4 w;
;                 w.x = pk_bf16(oa[0], oa[1]); w.y = pk_bf16(oa[2], oa[3]); w.z = pk_bf16(ob[0], ob[1]); w.w = pk_bf16(ob[2], ob[3]);
;                 if (ai == 0 && m == 0) rstd_finish(raw0, raw1, rn0, rn1);
;                 *(u32x4*)(O + (size_t)row * FF + col0) = w;
	v_mul_f32_e32 v228, 0xbfb8aa3b, v168
	v_pk_mul_f32 v[26:27], v[18:19], v[26:27]
	v_pk_mul_f32 v[28:29], v[20:21], v[28:29]
	v_pk_mul_f32 v[22:23], v[22:23], v[228:229] op_sel_hi:[1,0]
	v_pk_mul_f32 v[24:25], v[24:25], v[228:229] op_sel_hi:[1,0]
	v_pk_mul_f32 v[18:19], v[18:19], v[228:229] op_sel_hi:[1,0]
	v_pk_mul_f32 v[20:21], v[20:21], v[228:229] op_sel_hi:[1,0]
	v_exp_f32_e32 v22, v22
	v_exp_f32_e32 v23, v23
	v_exp_f32_e32 v24, v24
	v_exp_f32_e32 v25, v25
	v_exp_f32_e32 v18, v18
	v_exp_f32_e32 v19, v19
	v_exp_f32_e32 v20, v20
	v_exp_f32_e32 v21, v21
	v_pk_fma_f32 v[22:23], v[22:23], v[224:225], v[224:225] op_sel_hi:[1,0,0]
	v_pk_fma_f32 v[24:25], v[24:25], v[224:225], v[224:225] op_sel_hi:[1,0,0]
	v_pk_fma_f32 v[18:19], v[18:19], v[224:225], v[224:225] op_sel_hi:[1,0,0]
	v_pk_fma_f32 v[20:21], v[20:21], v[224:225], v[224:225] op_sel_hi:[1,0,0]
	v_rcp_f32_e32 v22, v22
	v_rcp_f32_e32 v23, v23
	v_rcp_f32_e32 v24, v24
	v_rcp_f32_e32 v25, v25
	v_rcp_f32_e32 v18, v18
	v_rcp_f32_e32 v19, v19
	v_rcp_f32_e32 v20, v20
	v_rcp_f32_e32 v21, v21
	v_pk_mul_f32 v[30:31], v[30:31], v[22:23]
	v_pk_mul_f32 v[32:33], v[32:33], v[24:25]
	v_pk_mul_f32 v[26:27], v[26:27], v[18:19]
	v_pk_mul_f32 v[28:29], v[28:29], v[20:21]
	v_cvt_pk_bf16_f32 v22, v30, v31
	v_cvt_pk_bf16_f32 v23, v32, v33
	v_cvt_pk_bf16_f32 v24, v26, v27
	v_cvt_pk_bf16_f32 v25, v28, v29
	v_add_u32_e32 v170, 0xdc000, v161
	global_store_dwordx4 v170, v[22:25], s[24:25]
	v_pk_mul_f32 v[14:15], v[6:7], v[14:15]
	v_pk_mul_f32 v[16:17], v[8:9], v[16:17]
	s_waitcnt lgkmcnt(0)
	v_mul_f32_e32 v228, 0xbfb8aa3b, v169
	v_pk_mul_f32 v[10:11], v[2:3], v[10:11]
	v_pk_mul_f32 v[12:13], v[4:5], v[12:13]
	v_pk_mul_f32 v[6:7], v[6:7], v[228:229] op_sel_hi:[1,0]
	v_pk_mul_f32 v[8:9], v[8:9], v[228:229] op_sel_hi:[1,0]
	v_pk_mul_f32 v[2:3], v[2:3], v[228:229] op_sel_hi:[1,0]
	v_pk_mul_f32 v[4:5], v[4:5], v[228:229] op_sel_hi:[1,0]
	v_exp_f32_e32 v6, v6
	v_exp_f32_e32 v7, v7
	v_exp_f32_e32 v8, v8
	v_exp_f32_e32 v9, v9
	v_exp_f32_e32 v2, v2
	v_exp_f32_e32 v3, v3
	v_exp_f32_e32 v4, v4
	v_exp_f32_e32 v5, v5
	v_pk_fma_f32 v[6:7], v[6:7], v[226:227], v[226:227] op_sel_hi:[1,0,0]
	v_pk_fma_f32 v[8:9], v[8:9], v[226:227], v[226:227] op_sel_hi:[1,0,0]
	v_pk_fma_f32 v[2:3], v[2:3], v[226:227], v[226:227] op_sel_hi:[1,0,0]
	v_pk_fma_f32 v[4:5], v[4:5], v[226:227], v[226:227] op_sel_hi:[1,0,0]
	v_rcp_f32_e32 v6, v6
	v_rcp_f32_e32 v7, v7
	v_rcp_f32_e32 v8, v8
	v_rcp_f32_e32 v9, v9
	v_rcp_f32_e32 v2, v2
	v_rcp_f32_e32 v3, v3
	v_rcp_f32_e32 v4, v4
	v_rcp_f32_e32 v5, v5
	v_pk_mul_f32 v[14:15], v[14:15], v[6:7]
	v_pk_mul_f32 v[16:17], v[16:17], v[8:9]
	v_pk_mul_f32 v[10:11], v[10:11], v[2:3]
	v_pk_mul_f32 v[12:13], v[12:13], v[4:5]
	v_cvt_pk_bf16_f32 v6, v14, v15
	v_cvt_pk_bf16_f32 v7, v16, v17
	v_cvt_pk_bf16_f32 v8, v10, v11
	v_cvt_pk_bf16_f32 v9, v12, v13
	v_add_u32_e32 v170, 0xf2000, v161
	global_store_dwordx4 v170, v[6:9], s[24:25]
	s_waitcnt vmcnt(8)
	v_mov_b32_e32 v122, v135
	v_mov_b32_e32 v123, v136
	v_mov_b32_e32 v135, v137
	v_mov_b32_e32 v124, v131
	v_mov_b32_e32 v125, v132
	v_mov_b32_e32 v131, v133
	v_pk_add_f32 v[122:123], v[122:123], v[134:135]
	v_pk_add_f32 v[124:125], v[124:125], v[130:131]
	v_mov_b32_e32 v126, v124
	v_mov_b32_e32 v127, v122
	v_mov_b32_e32 v122, v125
	v_pk_add_f32 v[122:123], v[126:127], v[122:123]
	v_pk_fma_f32 v[122:123], v[122:123], s[84:85], v[182:183] op_sel_hi:[1,0,0]
	v_mov_b32_e32 v252, v122
	v_mov_b32_e32 v253, v123
	v_rsq_f32_e32 v145, v123
	v_rsq_f32_e32 v144, v122
	s_cbranch_vccnz .LBB0_315
	s_andn2_b64 vcc, exec, s[2:3]
	s_cbranch_vccnz .LBB0_314
	s_barrier
	s_branch .LBB0_314
